# static priority raise (s_setprio 1) for waves 4-7 before each hyena main MFMA loop
# speedup vs baseline: 1.0045x; 1.0015x over previous
; template <int L>
; __device__ __forceinline__ void hy_conv(const bf16_t* F, const bf16_t* Bbuf, const bf16_t* Vbuf, bf16_t* Obuf, float skipv) {
;     ...
;     {
;         int d = -PADE - T0a; const int dlast = L - T0b - 32;
;         bf16x8 b0c = *(const bf16x8*)(bp0 + d), b1c = *(const bf16x8*)(bp1 + d), ac[4];
; #pragma unroll
;         for (int rho = 0; rho < 4; ++rho) ac[rho] = HY_AFR(rho, d);
;         for (; d < dlast; d += 32) {
;             const bf16x8 b0n = *(const bf16x8*)(bp0 + d + 32), b1n = *(const bf16x8*)(bp1 + d + 32); bf16x8 an[4];
; #pragma unroll
;             for (int rho = 0; rho < 4; ++rho) an[rho] = HY_AFR(rho, d + 32);
; #pragma unroll
;             for (int rho = 0; rho < 4; ++rho) {
;                 acc0[rho] = __builtin_amdgcn_mfma_f32_16x16x32_bf16(ac[rho], b0c, acc0[rho], 0, 0, 0);
;                 acc1[rho] = __builtin_amdgcn_mfma_f32_16x16x32_bf16(ac[rho], b1c, acc1[rho], 0, 0, 0); }
;             b0c = b0n; b1c = b1n;
; #pragma unroll
;             for (int rho = 0; rho < 4; ++rho) ac[rho] = an[rho];
;         }
.LBB0_467:
	s_or_b64 exec, exec, s[28:29]
	v_lshlrev_b32_e32 v53, 1, v50
	v_add_u32_e32 v52, v52, v53
	v_add_u32_e32 v49, v49, v53
	v_add_u32_e32 v53, 0x2000, v52
	ds_read_b128 v[84:87], v48
	ds_read_b128 v[48:51], v49 offset:512
	v_add_u32_e32 v54, 0x6180, v52
	ds_read2_b64 v[80:83], v53 offset1:1
	ds_read2_b64 v[76:79], v54 offset1:1
	v_add_u32_e32 v53, 0xa300, v52
	v_add_u32_e32 v52, 0xe480, v52
	ds_read2_b64 v[64:67], v53 offset1:1
	ds_read2_b64 v[52:55], v52 offset1:1
	v_sub_u32_e32 v238, 0xfe0, v233
	v_mov_b32_e32 v63, 0
	v_cmp_lt_i32_e32 vcc, v234, v238
	v_mov_b32_e32 v62, v63
	v_mov_b32_e32 v61, v63
	v_mov_b32_e32 v60, v63
	v_mov_b32_e32 v71, v63
	v_mov_b32_e32 v70, v63
	v_mov_b32_e32 v69, v63
	v_mov_b32_e32 v68, v63
	v_mov_b32_e32 v75, v63
	v_mov_b32_e32 v74, v63
	v_mov_b32_e32 v73, v63
	v_mov_b32_e32 v72, v63
	v_mov_b32_e32 v59, v63
	v_mov_b32_e32 v58, v63
	v_mov_b32_e32 v57, v63
	v_mov_b32_e32 v56, v63
	s_and_saveexec_b64 s[6:7], vcc
	s_cbranch_execz .LBB0_471
	v_lshlrev_b32_e32 v57, 4, v235
	v_add_u32_e32 v56, v237, v228
	v_and_b32_e32 v57, 0xfffffc00, v57
	v_sub_u32_e32 v56, v56, v57
	s_add_i32 s14, 0, 0x2040
	v_add_u32_e32 v235, s14, v56
	v_lshlrev_b32_e32 v56, 5, v236
	s_movk_i32 s14, 0x180
	v_and_or_b32 v56, v56, s14, v228
	v_lshlrev_b32_e32 v57, 1, v229
	v_readlane_b32 s14, v253, 59
	s_mov_b64 s[24:25], 0
	s_nop 0
	v_add3_u32 v236, v56, v57, s14
	v_mov_b32_e32 v56, 0
	v_mov_b32_e32 v57, v56
	v_mov_b32_e32 v58, v56
	v_mov_b32_e32 v59, v56
	v_mov_b32_e32 v72, v56
	v_mov_b32_e32 v73, v56
	v_mov_b32_e32 v74, v56
	v_mov_b32_e32 v75, v56
	v_mov_b32_e32 v68, v56
	v_mov_b32_e32 v69, v56
	v_mov_b32_e32 v70, v56
	v_mov_b32_e32 v71, v56
	v_mov_b32_e32 v60, v56
	v_mov_b32_e32 v61, v56
	v_mov_b32_e32 v62, v56
	v_mov_b32_e32 v63, v56
	v_cmp_lt_u32_e32 vcc, 255, v131
	s_nop 4
	s_cbranch_vccz .Lhy_prio_469
	s_setprio 1
.Lhy_prio_469:
	s_waitcnt lgkmcnt(0)
.LBB0_469:
	s_waitcnt lgkmcnt(8)
	v_mov_b64_e32 v[242:243], v[86:87]
	v_mov_b64_e32 v[240:241], v[84:85]
	v_mov_b64_e32 v[246:247], v[50:51]
	v_mov_b64_e32 v[244:245], v[48:49]
	v_add_u32_e32 v234, 32, v234
	v_cmp_ge_i32_e32 vcc, v234, v238
	s_or_b64 s[24:25], vcc, s[24:25]
	v_add_u32_e32 v84, 0xfffffe00, v236
	ds_read_b128 v[48:51], v236
	ds_read_b128 v[84:87], v84
	v_add_u32_e32 v236, 64, v236
	s_waitcnt lgkmcnt(8)
	v_mfma_f32_16x16x32_bf16 v[72:75], v[80:83], v[240:243], v[72:75]
	v_mfma_f32_16x16x32_bf16 v[44:47], v[80:83], v[244:247], v[44:47]
	ds_read_b64 v[82:83], v235 offset:8
	ds_read_b64 v[80:81], v235 offset:0
	s_waitcnt lgkmcnt(8)
	v_mfma_f32_16x16x32_bf16 v[68:71], v[76:79], v[240:243], v[68:71]
	v_mfma_f32_16x16x32_bf16 v[40:43], v[76:79], v[244:247], v[40:43]
	ds_read_b64 v[78:79], v235 offset:16776
	ds_read_b64 v[76:77], v235 offset:16768
	s_waitcnt lgkmcnt(8)
	v_mfma_f32_16x16x32_bf16 v[60:63], v[64:67], v[240:243], v[60:63]
	v_mfma_f32_16x16x32_bf16 v[36:39], v[64:67], v[244:247], v[36:39]
	ds_read_b64 v[66:67], v235 offset:33544
	ds_read_b64 v[64:65], v235 offset:33536
	s_waitcnt lgkmcnt(8)
	v_mfma_f32_16x16x32_bf16 v[56:59], v[52:55], v[240:243], v[56:59]
	v_mfma_f32_16x16x32_bf16 v[32:35], v[52:55], v[244:247], v[32:35]
	ds_read_b64 v[54:55], v235 offset:50312
	ds_read_b64 v[52:53], v235 offset:50304
	v_add_u32_e32 v235, 64, v235
	s_andn2_b64 exec, exec, s[24:25]
	s_cbranch_execnz .LBB0_469
	s_waitcnt lgkmcnt(0)
	s_or_b64 exec, exec, s[24:25]

; template <int L>
; __device__ __forceinline__ void hy_conv(const bf16_t* F, const bf16_t* Bbuf, const bf16_t* Vbuf, bf16_t* Obuf, float skipv) {
;     ...
;     {
;         int d = -PADE - T0a; const int dlast = L - T0b - 32;
;         bf16x8 b0c = *(const bf16x8*)(bp0 + d), b1c = *(const bf16x8*)(bp1 + d), ac[4];
; #pragma unroll
;         for (int rho = 0; rho < 4; ++rho) ac[rho] = HY_AFR(rho, d);
;         for (; d < dlast; d += 32) {
;             const bf16x8 b0n = *(const bf16x8*)(bp0 + d + 32), b1n = *(const bf16x8*)(bp1 + d + 32); bf16x8 an[4];
; #pragma unroll
;             for (int rho = 0; rho < 4; ++rho) an[rho] = HY_AFR(rho, d + 32);
; #pragma unroll
;             for (int rho = 0; rho < 4; ++rho) {
;                 acc0[rho] = __builtin_amdgcn_mfma_f32_16x16x32_bf16(ac[rho], b0c, acc0[rho], 0, 0, 0);
;                 acc1[rho] = __builtin_amdgcn_mfma_f32_16x16x32_bf16(ac[rho], b1c, acc1[rho], 0, 0, 0); }
;             b0c = b0n; b1c = b1n;
; #pragma unroll
;             for (int rho = 0; rho < 4; ++rho) ac[rho] = an[rho];
;         }
.LBB0_541:
	s_or_b64 exec, exec, s[28:29]
	v_lshlrev_b32_e32 v53, 1, v50
	v_add_u32_e32 v52, v52, v53
	v_add_u32_e32 v49, v49, v53
	v_add_u32_e32 v53, 0x2000, v52
	ds_read_b128 v[84:87], v48
	ds_read_b128 v[48:51], v49 offset:512
	v_add_u32_e32 v54, 0x6180, v52
	ds_read2_b64 v[80:83], v53 offset1:1
	ds_read2_b64 v[76:79], v54 offset1:1
	v_add_u32_e32 v53, 0xa300, v52
	v_add_u32_e32 v52, 0xe480, v52
	ds_read2_b64 v[64:67], v53 offset1:1
	ds_read2_b64 v[52:55], v52 offset1:1
	v_sub_u32_e32 v211, 0xfe0, v206
	v_mov_b32_e32 v63, 0
	v_cmp_lt_i32_e32 vcc, v207, v211
	v_mov_b32_e32 v62, v63
	v_mov_b32_e32 v61, v63
	v_mov_b32_e32 v60, v63
	v_mov_b32_e32 v71, v63
	v_mov_b32_e32 v70, v63
	v_mov_b32_e32 v69, v63
	v_mov_b32_e32 v68, v63
	v_mov_b32_e32 v75, v63
	v_mov_b32_e32 v74, v63
	v_mov_b32_e32 v73, v63
	v_mov_b32_e32 v72, v63
	v_mov_b32_e32 v59, v63
	v_mov_b32_e32 v58, v63
	v_mov_b32_e32 v57, v63
	v_mov_b32_e32 v56, v63
	s_and_saveexec_b64 s[6:7], vcc
	s_cbranch_execz .LBB0_545
	v_lshlrev_b32_e32 v57, 4, v208
	v_add_u32_e32 v56, v210, v201
	v_and_b32_e32 v57, 0xfffffc00, v57
	v_sub_u32_e32 v56, v56, v57
	s_add_i32 s14, 0, 0x2040
	v_add_u32_e32 v208, s14, v56
	v_lshlrev_b32_e32 v56, 5, v209
	s_movk_i32 s14, 0x180
	v_and_or_b32 v56, v56, s14, v201
	v_lshlrev_b32_e32 v57, 1, v202
	v_readlane_b32 s14, v253, 60
	s_mov_b64 s[24:25], 0
	s_nop 0
	v_add3_u32 v209, v56, v57, s14
	v_mov_b32_e32 v56, 0
	v_mov_b32_e32 v57, v56
	v_mov_b32_e32 v58, v56
	v_mov_b32_e32 v59, v56
	v_mov_b32_e32 v72, v56
	v_mov_b32_e32 v73, v56
	v_mov_b32_e32 v74, v56
	v_mov_b32_e32 v75, v56
	v_mov_b32_e32 v68, v56
	v_mov_b32_e32 v69, v56
	v_mov_b32_e32 v70, v56
	v_mov_b32_e32 v71, v56
	v_mov_b32_e32 v60, v56
	v_mov_b32_e32 v61, v56
	v_mov_b32_e32 v62, v56
	v_mov_b32_e32 v63, v56
	v_cmp_lt_u32_e32 vcc, 255, v131
	s_nop 4
	s_cbranch_vccz .Lhy_prio_543
	s_setprio 1
.Lhy_prio_543:
	s_waitcnt lgkmcnt(0)
.LBB0_543:
	s_waitcnt lgkmcnt(8)
	v_mov_b64_e32 v[214:215], v[86:87]
	v_mov_b64_e32 v[212:213], v[84:85]
	v_mov_b64_e32 v[218:219], v[50:51]
	v_mov_b64_e32 v[216:217], v[48:49]
	v_add_u32_e32 v207, 32, v207
	v_cmp_ge_i32_e32 vcc, v207, v211
	s_or_b64 s[24:25], vcc, s[24:25]
	v_add_u32_e32 v84, 0xfffffe00, v209
	ds_read_b128 v[48:51], v209
	ds_read_b128 v[84:87], v84
	v_add_u32_e32 v209, 64, v209
	s_waitcnt lgkmcnt(8)
	v_mfma_f32_16x16x32_bf16 v[72:75], v[80:83], v[212:215], v[72:75]
	v_mfma_f32_16x16x32_bf16 v[44:47], v[80:83], v[216:219], v[44:47]
	ds_read_b64 v[82:83], v208 offset:8
	ds_read_b64 v[80:81], v208 offset:0
	s_waitcnt lgkmcnt(8)
	v_mfma_f32_16x16x32_bf16 v[68:71], v[76:79], v[212:215], v[68:71]
	v_mfma_f32_16x16x32_bf16 v[40:43], v[76:79], v[216:219], v[40:43]
	ds_read_b64 v[78:79], v208 offset:16776
	ds_read_b64 v[76:77], v208 offset:16768
	s_waitcnt lgkmcnt(8)
	v_mfma_f32_16x16x32_bf16 v[60:63], v[64:67], v[212:215], v[60:63]
	v_mfma_f32_16x16x32_bf16 v[36:39], v[64:67], v[216:219], v[36:39]
	ds_read_b64 v[66:67], v208 offset:33544
	ds_read_b64 v[64:65], v208 offset:33536
	s_waitcnt lgkmcnt(8)
	v_mfma_f32_16x16x32_bf16 v[56:59], v[52:55], v[212:215], v[56:59]
	v_mfma_f32_16x16x32_bf16 v[32:35], v[52:55], v[216:219], v[32:35]
	ds_read_b64 v[54:55], v208 offset:50312
	ds_read_b64 v[52:53], v208 offset:50304
	v_add_u32_e32 v208, 64, v208
	s_andn2_b64 exec, exec, s[24:25]
	s_cbranch_execnz .LBB0_543
	s_waitcnt lgkmcnt(0)
	s_or_b64 exec, exec, s[24:25]

; template <int L>
; __device__ __forceinline__ void hy_conv(const bf16_t* F, const bf16_t* Bbuf, const bf16_t* Vbuf, bf16_t* Obuf, float skipv) {
;     ...
;     {
;         int d = -PADE - T0a; const int dlast = L - T0b - 32;
;         bf16x8 b0c = *(const bf16x8*)(bp0 + d), b1c = *(const bf16x8*)(bp1 + d), ac[4];
; #pragma unroll
;         for (int rho = 0; rho < 4; ++rho) ac[rho] = HY_AFR(rho, d);
;         for (; d < dlast; d += 32) {
;             const bf16x8 b0n = *(const bf16x8*)(bp0 + d + 32), b1n = *(const bf16x8*)(bp1 + d + 32); bf16x8 an[4];
; #pragma unroll
;             for (int rho = 0; rho < 4; ++rho) an[rho] = HY_AFR(rho, d + 32);
; #pragma unroll
;             for (int rho = 0; rho < 4; ++rho) {
;                 acc0[rho] = __builtin_amdgcn_mfma_f32_16x16x32_bf16(ac[rho], b0c, acc0[rho], 0, 0, 0);
;                 acc1[rho] = __builtin_amdgcn_mfma_f32_16x16x32_bf16(ac[rho], b1c, acc1[rho], 0, 0, 0); }
;             b0c = b0n; b1c = b1n;
; #pragma unroll
;             for (int rho = 0; rho < 4; ++rho) ac[rho] = an[rho];
;         }
.LBB0_645:
	s_or_b64 exec, exec, s[6:7]
	v_lshlrev_b32_e32 v53, 1, v50
	v_add_u32_e32 v52, v52, v53
	v_add_u32_e32 v49, v49, v53
	v_add_u32_e32 v53, 0x1100, v52
	ds_read_b128 v[56:59], v48 offset:34560
	ds_read_b128 v[48:51], v49 offset:34816
	v_add_u32_e32 v54, 0x3280, v52
	ds_read2_b64 v[84:87], v53 offset1:1
	ds_read2_b64 v[80:83], v54 offset1:1
	v_add_u32_e32 v53, 0x5400, v52
	v_add_u32_e32 v52, 0x7580, v52
	ds_read2_b64 v[72:75], v53 offset1:1
	ds_read2_b64 v[52:55], v52 offset1:1
	v_sub_u32_e32 v197, 0x7e0, v192
	v_mov_b32_e32 v67, 0
	v_cmp_lt_i32_e32 vcc, v193, v197
	v_mov_b32_e32 v66, v67
	v_mov_b32_e32 v65, v67
	v_mov_b32_e32 v64, v67
	v_mov_b32_e32 v71, v67
	v_mov_b32_e32 v70, v67
	v_mov_b32_e32 v69, v67
	v_mov_b32_e32 v68, v67
	v_mov_b32_e32 v79, v67
	v_mov_b32_e32 v78, v67
	v_mov_b32_e32 v77, v67
	v_mov_b32_e32 v76, v67
	v_mov_b32_e32 v63, v67
	v_mov_b32_e32 v62, v67
	v_mov_b32_e32 v61, v67
	v_mov_b32_e32 v60, v67
	s_and_saveexec_b64 s[6:7], vcc
	s_cbranch_execz .LBB0_649
	v_lshlrev_b32_e32 v61, 3, v194
	v_add_u32_e32 v60, v196, v187
	v_and_b32_e32 v61, 0xfffffe00, v61
	v_sub_u32_e32 v60, v60, v61
	s_add_i32 s14, 0, 0x1140
	v_add_u32_e32 v194, s14, v60
	v_lshlrev_b32_e32 v60, 4, v195
	s_movk_i32 s14, 0x80
	v_and_or_b32 v60, v60, s14, v187
	v_lshlrev_b32_e32 v61, 1, v188
	v_readlane_b32 s14, v253, 63
	s_mov_b64 s[24:25], 0
	s_nop 0
	v_add3_u32 v195, v60, v61, s14
	v_mov_b32_e32 v60, 0
	v_mov_b32_e32 v61, v60
	v_mov_b32_e32 v62, v60
	v_mov_b32_e32 v63, v60
	v_mov_b32_e32 v76, v60
	v_mov_b32_e32 v77, v60
	v_mov_b32_e32 v78, v60
	v_mov_b32_e32 v79, v60
	v_mov_b32_e32 v68, v60
	v_mov_b32_e32 v69, v60
	v_mov_b32_e32 v70, v60
	v_mov_b32_e32 v71, v60
	v_mov_b32_e32 v64, v60
	v_mov_b32_e32 v65, v60
	v_mov_b32_e32 v66, v60
	v_mov_b32_e32 v67, v60
	v_cmp_lt_u32_e32 vcc, 255, v131
	s_nop 4
	s_cbranch_vccz .Lhy_prio_647
	s_setprio 1
.Lhy_prio_647:
	s_waitcnt lgkmcnt(0)
.LBB0_647:
	s_waitcnt lgkmcnt(8)
	v_mov_b64_e32 v[200:201], v[58:59]
	v_mov_b64_e32 v[198:199], v[56:57]
	v_mov_b64_e32 v[204:205], v[50:51]
	v_mov_b64_e32 v[202:203], v[48:49]
	v_add_u32_e32 v193, 32, v193
	v_cmp_ge_i32_e32 vcc, v193, v197
	s_or_b64 s[24:25], vcc, s[24:25]
	s_nop 0
	ds_read_b128 v[56:59], v195
	ds_read_b128 v[48:51], v195 offset:256
	v_add_u32_e32 v195, 64, v195
	s_waitcnt lgkmcnt(8)
	v_mfma_f32_16x16x32_bf16 v[76:79], v[84:87], v[198:201], v[76:79]
	v_mfma_f32_16x16x32_bf16 v[40:43], v[84:87], v[202:205], v[40:43]
	ds_read_b64 v[86:87], v194 offset:8
	ds_read_b64 v[84:85], v194 offset:0
	s_waitcnt lgkmcnt(8)
	v_mfma_f32_16x16x32_bf16 v[68:71], v[80:83], v[198:201], v[68:71]
	v_mfma_f32_16x16x32_bf16 v[36:39], v[80:83], v[202:205], v[36:39]
	ds_read_b64 v[82:83], v194 offset:8584
	ds_read_b64 v[80:81], v194 offset:8576
	s_waitcnt lgkmcnt(8)
	v_mfma_f32_16x16x32_bf16 v[64:67], v[72:75], v[198:201], v[64:67]
	v_mfma_f32_16x16x32_bf16 v[44:47], v[72:75], v[202:205], v[44:47]
	ds_read_b64 v[74:75], v194 offset:17160
	ds_read_b64 v[72:73], v194 offset:17152
	s_waitcnt lgkmcnt(8)
	v_mfma_f32_16x16x32_bf16 v[60:63], v[52:55], v[198:201], v[60:63]
	v_mfma_f32_16x16x32_bf16 v[32:35], v[52:55], v[202:205], v[32:35]
	ds_read_b64 v[54:55], v194 offset:25736
	ds_read_b64 v[52:53], v194 offset:25728
	v_add_u32_e32 v194, 64, v194
	s_andn2_b64 exec, exec, s[24:25]
	s_cbranch_execnz .LBB0_647
	s_waitcnt lgkmcnt(0)
	s_or_b64 exec, exec, s[24:25]

; template <int L>
; __device__ __forceinline__ void hy_conv(const bf16_t* F, const bf16_t* Bbuf, const bf16_t* Vbuf, bf16_t* Obuf, float skipv) {
;     ...
;     {
;         int d = -PADE - T0a; const int dlast = L - T0b - 32;
;         bf16x8 b0c = *(const bf16x8*)(bp0 + d), b1c = *(const bf16x8*)(bp1 + d), ac[4];
; #pragma unroll
;         for (int rho = 0; rho < 4; ++rho) ac[rho] = HY_AFR(rho, d);
;         for (; d < dlast; d += 32) {
;             const bf16x8 b0n = *(const bf16x8*)(bp0 + d + 32), b1n = *(const bf16x8*)(bp1 + d + 32); bf16x8 an[4];
; #pragma unroll
;             for (int rho = 0; rho < 4; ++rho) an[rho] = HY_AFR(rho, d + 32);
; #pragma unroll
;             for (int rho = 0; rho < 4; ++rho) {
;                 acc0[rho] = __builtin_amdgcn_mfma_f32_16x16x32_bf16(ac[rho], b0c, acc0[rho], 0, 0, 0);
;                 acc1[rho] = __builtin_amdgcn_mfma_f32_16x16x32_bf16(ac[rho], b1c, acc1[rho], 0, 0, 0); }
;             b0c = b0n; b1c = b1n;
; #pragma unroll
;             for (int rho = 0; rho < 4; ++rho) ac[rho] = an[rho];
;         }
.LBB0_691:
	s_or_b64 exec, exec, s[6:7]
	v_lshlrev_b32_e32 v53, 1, v50
	v_add_u32_e32 v52, v52, v53
	v_add_u32_e32 v49, v49, v53
	v_add_u32_e32 v53, 0x1100, v52
	ds_read_b128 v[84:87], v48 offset:256
	ds_read_b128 v[48:51], v49 offset:512
	v_add_u32_e32 v54, 0x3280, v52
	ds_read2_b64 v[80:83], v53 offset1:1
	ds_read2_b64 v[76:79], v54 offset1:1
	v_add_u32_e32 v53, 0x5400, v52
	v_add_u32_e32 v52, 0x7580, v52
	ds_read2_b64 v[64:67], v53 offset1:1
	ds_read2_b64 v[52:55], v52 offset1:1
	v_sub_u32_e32 v182, 0x7e0, v159
	v_mov_b32_e32 v63, 0
	v_cmp_lt_i32_e32 vcc, v160, v182
	v_mov_b32_e32 v62, v63
	v_mov_b32_e32 v61, v63
	v_mov_b32_e32 v60, v63
	v_mov_b32_e32 v71, v63
	v_mov_b32_e32 v70, v63
	v_mov_b32_e32 v69, v63
	v_mov_b32_e32 v68, v63
	v_mov_b32_e32 v75, v63
	v_mov_b32_e32 v74, v63
	v_mov_b32_e32 v73, v63
	v_mov_b32_e32 v72, v63
	v_mov_b32_e32 v59, v63
	v_mov_b32_e32 v58, v63
	v_mov_b32_e32 v57, v63
	v_mov_b32_e32 v56, v63
	s_and_saveexec_b64 s[6:7], vcc
	s_cbranch_execz .LBB0_695
	v_lshlrev_b32_e32 v57, 3, v161
	v_add_u32_e32 v56, v181, v154
	v_and_b32_e32 v57, 0xfffffe00, v57
	v_sub_u32_e32 v56, v56, v57
	s_add_i32 s14, 0, 0x1140
	v_add_u32_e32 v161, s14, v56
	v_lshlrev_b32_e32 v56, 4, v180
	s_movk_i32 s14, 0x80
	v_and_or_b32 v56, v56, s14, v154
	v_lshlrev_b32_e32 v57, 1, v155
	v_readlane_b32 s14, v254, 0
	s_mov_b64 s[24:25], 0
	s_nop 0
	v_add3_u32 v180, v56, v57, s14
	v_mov_b32_e32 v56, 0
	v_mov_b32_e32 v57, v56
	v_mov_b32_e32 v58, v56
	v_mov_b32_e32 v59, v56
	v_mov_b32_e32 v72, v56
	v_mov_b32_e32 v73, v56
	v_mov_b32_e32 v74, v56
	v_mov_b32_e32 v75, v56
	v_mov_b32_e32 v68, v56
	v_mov_b32_e32 v69, v56
	v_mov_b32_e32 v70, v56
	v_mov_b32_e32 v71, v56
	v_mov_b32_e32 v60, v56
	v_mov_b32_e32 v61, v56
	v_mov_b32_e32 v62, v56
	v_mov_b32_e32 v63, v56
	v_cmp_lt_u32_e32 vcc, 255, v131
	s_nop 4
	s_cbranch_vccz .Lhy_prio_693
	s_setprio 1
.Lhy_prio_693:
	s_waitcnt lgkmcnt(0)
.LBB0_693:
	s_waitcnt lgkmcnt(8)
	v_mov_b64_e32 v[186:187], v[86:87]
	v_mov_b64_e32 v[184:185], v[84:85]
	v_mov_b64_e32 v[190:191], v[50:51]
	v_mov_b64_e32 v[188:189], v[48:49]
	v_add_u32_e32 v160, 32, v160
	v_cmp_ge_i32_e32 vcc, v160, v182
	s_or_b64 s[24:25], vcc, s[24:25]
	v_add_u32_e32 v84, 0xffffff00, v180
	ds_read_b128 v[48:51], v180
	ds_read_b128 v[84:87], v84
	v_add_u32_e32 v180, 64, v180
	s_waitcnt lgkmcnt(8)
	v_mfma_f32_16x16x32_bf16 v[72:75], v[80:83], v[184:187], v[72:75]
	v_mfma_f32_16x16x32_bf16 v[40:43], v[80:83], v[188:191], v[40:43]
	ds_read_b64 v[82:83], v161 offset:8
	ds_read_b64 v[80:81], v161 offset:0
	s_waitcnt lgkmcnt(8)
	v_mfma_f32_16x16x32_bf16 v[68:71], v[76:79], v[184:187], v[68:71]
	v_mfma_f32_16x16x32_bf16 v[36:39], v[76:79], v[188:191], v[36:39]
	ds_read_b64 v[78:79], v161 offset:8584
	ds_read_b64 v[76:77], v161 offset:8576
	s_waitcnt lgkmcnt(8)
	v_mfma_f32_16x16x32_bf16 v[60:63], v[64:67], v[184:187], v[60:63]
	v_mfma_f32_16x16x32_bf16 v[44:47], v[64:67], v[188:191], v[44:47]
	ds_read_b64 v[66:67], v161 offset:17160
	ds_read_b64 v[64:65], v161 offset:17152
	s_waitcnt lgkmcnt(8)
	v_mfma_f32_16x16x32_bf16 v[56:59], v[52:55], v[184:187], v[56:59]
	v_mfma_f32_16x16x32_bf16 v[32:35], v[52:55], v[188:191], v[32:35]
	ds_read_b64 v[54:55], v161 offset:25736
	ds_read_b64 v[52:53], v161 offset:25728
	v_add_u32_e32 v161, 64, v161
	s_andn2_b64 exec, exec, s[24:25]
	s_cbranch_execnz .LBB0_693
	s_waitcnt lgkmcnt(0)
	s_or_b64 exec, exec, s[24:25]
